# attention without s_setprio (G2 deferral already offsets the CU partners)
# baseline (speedup 1.0000x reference)
; DI void phase_even_c(const Ctx& c, int l, bf16* lds) {
;     ...
;   xcd_items(512, [&](int it) { attn_item(c, it, lds); });
.Lattn_pre:
	v_readlane_b32 vcc_lo, v252, 32
	s_cmp_ge_u32 vcc_lo, 0x10000
	s_cbranch_scc0 .Lattn_noprio
	s_setprio 0
